# attention unit epilogue: lam/lsum division done once per row before the LDS exchange (bit-identical) instead of 16 IEEE divisions per lane after it
# speedup vs baseline: 1.0054x; 1.0054x over previous
; #define LAS __attribute__((address_space(3)))
; __device__ __forceinline__ void attn_phase(LAS unsigned char* lds, const AttnArgs& a, int tid_in) {
;     ...
;         lsum += __shfl_xor(lsum, 32);
;         if (hi == 0) LW[r32] = lsum;
;         asm volatile("s_waitcnt lgkmcnt(0)" ::: "memory");
;         LAS float* S = (LAS float*)lds;
;         float li[16];
; #pragma unroll
;         for (int r = 0; r < 16; ++r) li[r] = (c == 0 ? 1.0f : a.lam) / LW[(r & 3) + 8 * (r >> 2) + 4 * hi];
.LBB0_592:
	s_mul_i32 s4, s6, 0x5000
	v_add_u32_e32 v0, s4, v225
	ds_read_b64_tr_b16 v[4:5], v0 offset:34816
	ds_read_b64_tr_b16 v[6:7], v0 offset:37376
	ds_read_b64_tr_b16 v[8:9], v0 offset:34880
	ds_read_b64_tr_b16 v[10:11], v0 offset:37440
	ds_read_b64_tr_b16 v[12:13], v0 offset:34944
	ds_read_b64_tr_b16 v[14:15], v0 offset:37504
	ds_read_b64_tr_b16 v[96:97], v0 offset:35008
	ds_read_b64_tr_b16 v[98:99], v0 offset:37568
	s_waitcnt lgkmcnt(6)
	v_mfma_f32_32x32x16_bf16 v[64:79], v[188:191], v[4:7], v[64:79]
	ds_read_b64_tr_b16 v[4:5], v0 offset:39936
	ds_read_b64_tr_b16 v[6:7], v0 offset:42496
	s_waitcnt lgkmcnt(6)
	v_mfma_f32_32x32x16_bf16 v[80:95], v[188:191], v[8:11], v[80:95]
	ds_read_b64_tr_b16 v[8:9], v0 offset:40000
	ds_read_b64_tr_b16 v[10:11], v0 offset:42560
	s_waitcnt lgkmcnt(6)
	v_mfma_f32_32x32x16_bf16 v[48:63], v[188:191], v[12:15], v[48:63]
	ds_read_b64_tr_b16 v[12:13], v0 offset:40064
	ds_read_b64_tr_b16 v[14:15], v0 offset:42624
	s_waitcnt lgkmcnt(6)
	v_mfma_f32_32x32x16_bf16 v[32:47], v[188:191], v[96:99], v[32:47]
	ds_read_b64_tr_b16 v[96:97], v0 offset:40128
	ds_read_b64_tr_b16 v[98:99], v0 offset:42688
	s_waitcnt lgkmcnt(6)
	v_mfma_f32_32x32x16_bf16 v[64:79], v[184:187], v[4:7], v[64:79]
	ds_read_b64_tr_b16 v[4:5], v0 offset:45056
	ds_read_b64_tr_b16 v[6:7], v0 offset:47616
	s_waitcnt lgkmcnt(6)
	v_mfma_f32_32x32x16_bf16 v[80:95], v[184:187], v[8:11], v[80:95]
	ds_read_b64_tr_b16 v[8:9], v0 offset:45120
	ds_read_b64_tr_b16 v[10:11], v0 offset:47680
	s_waitcnt lgkmcnt(6)
	v_mfma_f32_32x32x16_bf16 v[48:63], v[184:187], v[12:15], v[48:63]
	ds_read_b64_tr_b16 v[12:13], v0 offset:45184
	ds_read_b64_tr_b16 v[14:15], v0 offset:47744
	s_waitcnt lgkmcnt(6)
	v_mfma_f32_32x32x16_bf16 v[32:47], v[184:187], v[96:99], v[32:47]
	ds_read_b64_tr_b16 v[96:97], v0 offset:45248
	ds_read_b64_tr_b16 v[98:99], v0 offset:47808
	s_waitcnt lgkmcnt(6)
	v_mfma_f32_32x32x16_bf16 v[64:79], v[180:183], v[4:7], v[64:79]
	ds_read_b64_tr_b16 v[4:5], v0 offset:50176
	ds_read_b64_tr_b16 v[6:7], v0 offset:52736
	s_waitcnt lgkmcnt(6)
	v_mfma_f32_32x32x16_bf16 v[80:95], v[180:183], v[8:11], v[80:95]
	ds_read_b64_tr_b16 v[8:9], v0 offset:50240
	ds_read_b64_tr_b16 v[10:11], v0 offset:52800
	s_waitcnt lgkmcnt(6)
	v_mfma_f32_32x32x16_bf16 v[48:63], v[180:183], v[12:15], v[48:63]
	ds_read_b64_tr_b16 v[12:13], v0 offset:50304
	ds_read_b64_tr_b16 v[14:15], v0 offset:52864
	s_waitcnt lgkmcnt(6)
	v_mfma_f32_32x32x16_bf16 v[32:47], v[180:183], v[96:99], v[32:47]
	ds_read_b64_tr_b16 v[96:97], v0 offset:50368
	ds_read_b64_tr_b16 v[98:99], v0 offset:52928
	v_xor_b32_e32 v0, 32, v215
	s_waitcnt lgkmcnt(6)
	v_mfma_f32_32x32x16_bf16 v[64:79], v[176:179], v[4:7], v[64:79]
	v_cmp_lt_i32_e32 vcc, v0, v217
	s_waitcnt lgkmcnt(0)
	s_barrier
	v_cndmask_b32_e32 v0, v215, v0, vcc
	v_lshlrev_b32_e32 v0, 2, v0
	ds_bpermute_b32 v0, v0, v2
	s_waitcnt lgkmcnt(0)
	v_mfma_f32_32x32x16_bf16 v[80:95], v[176:179], v[8:11], v[80:95]
	v_mfma_f32_32x32x16_bf16 v[48:63], v[176:179], v[12:15], v[48:63]
	v_mfma_f32_32x32x16_bf16 v[32:47], v[176:179], v[96:99], v[32:47]
	s_and_saveexec_b64 s[4:5], s[38:39]
	v_add_f32_e32 v0, v2, v0
	v_div_scale_f32 v14, vcc, v0, v0, v232
	v_rcp_f32_e32 v15, v14
	s_nop 0
	v_fma_f32 v100, -v14, v15, 1.0
	v_fmac_f32_e32 v15, v100, v15
	v_div_scale_f32 v100, vcc, v232, v0, v232
	v_mul_f32_e32 v101, v100, v15
	v_fma_f32 v96, -v14, v101, v100
	v_fmac_f32_e32 v101, v96, v15
	v_fma_f32 v14, -v14, v101, v100
	v_div_fmas_f32 v14, v14, v15, v101
	v_div_fixup_f32 v97, v14, v0, v232
	ds_write_b32 v226, v97
	s_or_b64 exec, exec, s[4:5]
	s_waitcnt lgkmcnt(0)
	ds_read_b128 v[96:99], v230
	ds_read_b128 v[10:13], v230 offset:32
	ds_read_b128 v[6:9], v230 offset:64
	ds_read_b128 v[2:5], v230 offset:96
	s_and_saveexec_b64 s[4:5], s[36:37]
	s_cbranch_execz .LBB0_602
	s_mov_b32 s6, 0
	s_mov_b64 s[40:41], 0
	s_branch .LBB0_598

; #define LAS __attribute__((address_space(3)))
; #define A_FETCH(res) do { res = 0xffffffffu; \
;             for (unsigned i_ = 0; i_ < 8u && res == 0xffffffffu; ++i_) { const unsigned j_ = (xcc + i_) & 7u; \
;                 if (dead & (1u << j_)) continue; \
;                 const unsigned k_ = atomicAdd(a.ctr + 32 * j_, 1u); \
;                 if (k_ < 2u * NQB) res = (j_ << 8) | k_; else dead |= 1u << j_; } } while (0)
; __device__ __forceinline__ void attn_phase(LAS unsigned char* lds, const AttnArgs& a, int tid_in) {
;     ...
;         LAS float* S = (LAS float*)lds;
;         float li[16];
; #pragma unroll
;         for (int r = 0; r < 16; ++r) li[r] = (c == 0 ? 1.0f : a.lam) / LW[(r & 3) + 8 * (r >> 2) + 4 * hi];
;         if (tid == 0) { unsigned res; A_FETCH(res); *sU = res; }
;         if (c == 1) {
; #pragma unroll
;             for (int db = 0; db < 4; ++db)
; #pragma unroll
;                 for (int r = 0; r < 16; ++r) S[(32 * rg + (r & 3) + 8 * (r >> 2) + 4 * hi) * SSTR + 32 * db + r32] = o[db][r] * li[r];
;         }
.LBB0_602:
	s_or_b64 exec, exec, s[4:5]
	s_waitcnt lgkmcnt(0)
	v_mov_b32_e32 v14, v96
	v_mov_b32_e32 v15, v97
	v_mov_b32_e32 v96, v98
	v_mov_b32_e32 v97, v99
	s_andn2_b64 vcc, exec, s[14:15]
	s_cbranch_vccnz .LBB0_604
	v_mul_f32_e32 v0, v64, v14
	v_mul_f32_e32 v113, v80, v14
	v_mul_f32_e32 v98, v65, v15
	ds_write2_b32 v231, v0, v113 offset1:32
	v_mul_f32_e32 v0, v81, v15
	v_mul_f32_e32 v99, v66, v96
	ds_write2_b32 v231, v98, v0 offset0:132 offset1:164
	v_mul_f32_e32 v0, v82, v96
	v_add_u32_e32 v98, 0x400, v231
	v_mul_f32_e32 v100, v67, v97
	ds_write2_b32 v98, v99, v0 offset0:8 offset1:40
	v_mul_f32_e32 v0, v83, v97
	v_mul_f32_e32 v101, v68, v10
	ds_write2_b32 v98, v100, v0 offset0:140 offset1:172
	v_mul_f32_e32 v0, v84, v10
	v_add_u32_e32 v99, 0x1000, v231
	v_mul_f32_e32 v102, v69, v11
	ds_write2_b32 v99, v101, v0 offset0:32 offset1:64
	v_mul_f32_e32 v0, v85, v11
	v_mul_f32_e32 v103, v70, v12
	ds_write2_b32 v99, v102, v0 offset0:164 offset1:196
	v_mul_f32_e32 v0, v86, v12
	v_add_u32_e32 v100, 0x1400, v231
	v_mul_f32_e32 v104, v71, v13
	ds_write2_b32 v100, v103, v0 offset0:40 offset1:72
	v_mul_f32_e32 v0, v87, v13
	v_mul_f32_e32 v105, v72, v6
	ds_write2_b32 v100, v104, v0 offset0:172 offset1:204
	v_mul_f32_e32 v0, v88, v6
	v_add_u32_e32 v101, 0x2000, v231
	v_mul_f32_e32 v106, v73, v7
	ds_write2_b32 v101, v105, v0 offset0:64 offset1:96
	v_mul_f32_e32 v0, v89, v7
	v_mul_f32_e32 v107, v74, v8
	ds_write2_b32 v101, v106, v0 offset0:196 offset1:228
	v_mul_f32_e32 v0, v90, v8
	v_add_u32_e32 v102, 0x2400, v231
	v_mul_f32_e32 v108, v75, v9
	ds_write2_b32 v102, v107, v0 offset0:72 offset1:104
	v_mul_f32_e32 v0, v91, v9
	v_mul_f32_e32 v109, v76, v2
	ds_write2_b32 v102, v108, v0 offset0:204 offset1:236
	v_mul_f32_e32 v0, v92, v2
	v_add_u32_e32 v103, 0x3000, v231
	v_mul_f32_e32 v110, v77, v3
	ds_write2_b32 v103, v109, v0 offset0:96 offset1:128
	v_mul_f32_e32 v0, v93, v3
	v_add_u32_e32 v104, 0x3200, v231
	v_mul_f32_e32 v111, v78, v4
	ds_write2_b32 v104, v110, v0 offset0:100 offset1:132
	v_mul_f32_e32 v0, v94, v4
	v_add_u32_e32 v104, 0x3400, v231
	v_mul_f32_e32 v112, v79, v5
	ds_write2_b32 v104, v111, v0 offset0:104 offset1:136
	v_mul_f32_e32 v0, v95, v5
	v_add_u32_e32 v105, 0x3600, v231
	ds_write2_b32 v105, v112, v0 offset0:108 offset1:140
	v_mul_f32_e32 v0, v48, v14
	v_mul_f32_e32 v120, v32, v14
	v_mul_f32_e32 v105, v49, v15
	ds_write2_b32 v231, v0, v120 offset0:64 offset1:96
	v_mul_f32_e32 v0, v33, v15
	v_mul_f32_e32 v106, v50, v96
	ds_write2_b32 v231, v105, v0 offset0:196 offset1:228
	v_mul_f32_e32 v0, v34, v96
	v_mul_f32_e32 v107, v51, v97
	ds_write2_b32 v98, v106, v0 offset0:72 offset1:104
	v_mul_f32_e32 v0, v35, v97
	v_mul_f32_e32 v108, v52, v10
	ds_write2_b32 v98, v107, v0 offset0:204 offset1:236
	v_mul_f32_e32 v0, v36, v10
	v_mul_f32_e32 v109, v53, v11
	ds_write2_b32 v99, v108, v0 offset0:96 offset1:128
	v_mul_f32_e32 v0, v37, v11
	v_add_u32_e32 v98, 0x1200, v231
	v_mul_f32_e32 v110, v54, v12
	ds_write2_b32 v98, v109, v0 offset0:100 offset1:132
	v_mul_f32_e32 v0, v38, v12
	v_mul_f32_e32 v111, v55, v13
	ds_write2_b32 v100, v110, v0 offset0:104 offset1:136
	v_mul_f32_e32 v0, v39, v13
	v_add_u32_e32 v98, 0x1600, v231
	v_mul_f32_e32 v112, v56, v6
	ds_write2_b32 v98, v111, v0 offset0:108 offset1:140
	v_mul_f32_e32 v0, v40, v6
	v_mul_f32_e32 v113, v57, v7
	ds_write2_b32 v101, v112, v0 offset0:128 offset1:160
	v_mul_f32_e32 v0, v41, v7
	v_mul_f32_e32 v114, v58, v8
	ds_write2_b32 v102, v113, v0 offset0:4 offset1:36
	v_mul_f32_e32 v0, v42, v8
	v_mul_f32_e32 v115, v59, v9
	ds_write2_b32 v102, v114, v0 offset0:136 offset1:168
	v_mul_f32_e32 v0, v43, v9
	v_add_u32_e32 v98, 0x2800, v231
	v_mul_f32_e32 v116, v60, v2
	ds_write2_b32 v98, v115, v0 offset0:12 offset1:44
	v_mul_f32_e32 v0, v44, v2
	v_mul_f32_e32 v117, v61, v3
	ds_write2_b32 v103, v116, v0 offset0:160 offset1:192
	v_mul_f32_e32 v0, v45, v3
	v_mul_f32_e32 v118, v62, v4
	ds_write2_b32 v104, v117, v0 offset0:36 offset1:68
	v_mul_f32_e32 v0, v46, v4
	v_mul_f32_e32 v119, v63, v5
	ds_write2_b32 v104, v118, v0 offset0:168 offset1:200
	v_mul_f32_e32 v0, v47, v5
	v_add_u32_e32 v98, 0x3800, v231
	ds_write2_b32 v98, v119, v0 offset0:44 offset1:76
